# dual-tile mainloops without the per-visit s_sleep stagger of the second resident block (phases 1, 7, 9)
# baseline (speedup 1.0000x reference)
.LBB0_104:
	v_lshrrev_b32_e32 v78, 3, v168
	v_lshrrev_b32_e32 v79, 4, v168
	v_xor_b32_e32 v79, v79, v168
	v_and_b32_e32 v79, 7, v79
	v_lshlrev_b32_e32 v79, 4, v79
	v_lshl_or_b32 v64, v78, 11, v79
	v_add_u32_e32 v66, 0x10000, v64
	v_add_u32_e32 v67, 0x20000, v64
	v_add_u32_e32 v77, 0x30000, v64
	s_load_dwordx2 s[90:91], s[0:1], 0xa0
	s_load_dwordx2 s[92:93], s[0:1], 0xa8
	v_lshrrev_b32_e32 v79, 6, v168
	s_nop 1
	v_readfirstlane_b32 s97, v79
	s_nop 3
	s_lshl_b32 s96, s97, 10
	s_add_u32 s96, s96, 16
	s_add_u32 s94, s66, s67
	s_cmp_lt_i32 s94, s68
	s_cselect_b32 s95, 1, 0
	s_cmp_lg_u64 s[8:9], 0
	s_cselect_b32 s95, 0, s95
	s_cmp_ge_u32 s94, 0x180
	s_cselect_b32 s97, 1, 0
	s_mul_i32 s100, s97, 0x180
	s_sub_u32 s100, s94, s100
	s_lshr_b32 s101, s100, 3
	s_and_b32 s100, s100, 7
	s_lshl_b32 s97, s97, 3
	s_add_u32 s100, s100, s97
	s_add_u32 s100, s100, s3
	s_cmp_lg_u32 s100, s60
	s_cselect_b32 s95, 0, s95
	s_cmp_eq_u32 s95, 1
	s_cselect_b32 s101, s101, s58
	s_mov_b32 s83, s101
	s_waitcnt lgkmcnt(0)
	s_lshl_b32 s101, s101, 18
	s_add_u32 s98, s92, s101
	s_addc_u32 s99, s93, 0
	s_lshl_b32 s94, s58, 18
	s_add_u32 s92, s92, s94
	s_addc_u32 s93, s93, 0
	s_lshl_b32 s94, s60, 18
	s_add_u32 s90, s90, s94
	s_addc_u32 s91, s91, 0
	s_barrier
	s_add_u32 m0, s96, 0x0
	s_nop 0
	global_load_lds_dwordx4 v64, s[90:91]
	s_add_u32 m0, s96, 0x1000
	s_nop 0
	global_load_lds_dwordx4 v66, s[90:91]
	s_add_u32 m0, s96, 0x2000
	s_nop 0
	global_load_lds_dwordx4 v67, s[90:91]
	s_add_u32 m0, s96, 0x3000
	s_nop 0
	global_load_lds_dwordx4 v77, s[90:91]
	s_add_u32 m0, s96, 0x8000
	s_nop 0
	global_load_lds_dwordx4 v64, s[92:93]
	s_add_u32 m0, s96, 0x9000
	s_nop 0
	global_load_lds_dwordx4 v66, s[92:93]
	s_add_u32 m0, s96, 0xa000
	s_nop 0
	global_load_lds_dwordx4 v67, s[92:93]
	s_add_u32 m0, s96, 0xb000
	s_nop 0
	global_load_lds_dwordx4 v77, s[92:93]
	s_add_u32 m0, s96, 0xc000
	s_nop 0
	global_load_lds_dwordx4 v64, s[98:99]
	s_add_u32 m0, s96, 0xd000
	s_nop 0
	global_load_lds_dwordx4 v66, s[98:99]
	s_add_u32 m0, s96, 0xe000
	s_nop 0
	global_load_lds_dwordx4 v67, s[98:99]
	s_add_u32 m0, s96, 0xf000
	s_nop 0
	global_load_lds_dwordx4 v77, s[98:99]
	s_add_u32 s90, s90, 0x80
	s_addc_u32 s91, s91, 0
	s_add_u32 s92, s92, 0x80
	s_addc_u32 s93, s93, 0
	s_add_u32 s98, s98, 0x80
	s_addc_u32 s99, s99, 0
	v_mov_b32_e32 v56, 0
	v_mov_b32_e32 v57, v56
	v_mov_b32_e32 v58, v56
	v_mov_b32_e32 v59, v56
	v_mov_b32_e32 v48, v56
	v_mov_b32_e32 v49, v56
	v_mov_b32_e32 v50, v56
	v_mov_b32_e32 v51, v56
	v_mov_b32_e32 v60, v56
	v_mov_b32_e32 v61, v56
	v_mov_b32_e32 v62, v56
	v_mov_b32_e32 v63, v56
	v_mov_b32_e32 v52, v56
	v_mov_b32_e32 v53, v56
	v_mov_b32_e32 v54, v56
	v_mov_b32_e32 v55, v56
	v_mov_b32_e32 v40, v56
	v_mov_b32_e32 v41, v56
	v_mov_b32_e32 v42, v56
	v_mov_b32_e32 v43, v56
	v_mov_b32_e32 v32, v56
	v_mov_b32_e32 v33, v56
	v_mov_b32_e32 v34, v56
	v_mov_b32_e32 v35, v56
	v_mov_b32_e32 v44, v56
	v_mov_b32_e32 v45, v56
	v_mov_b32_e32 v46, v56
	v_mov_b32_e32 v47, v56
	v_mov_b32_e32 v36, v56
	v_mov_b32_e32 v37, v56
	v_mov_b32_e32 v38, v56
	v_mov_b32_e32 v39, v56
	v_mov_b32_e32 v24, v56
	v_mov_b32_e32 v25, v56
	v_mov_b32_e32 v26, v56
	v_mov_b32_e32 v27, v56
	v_mov_b32_e32 v16, v56
	v_mov_b32_e32 v17, v56
	v_mov_b32_e32 v18, v56
	v_mov_b32_e32 v19, v56
	v_mov_b32_e32 v28, v56
	v_mov_b32_e32 v29, v56
	v_mov_b32_e32 v30, v56
	v_mov_b32_e32 v31, v56
	v_mov_b32_e32 v20, v56
	v_mov_b32_e32 v21, v56
	v_mov_b32_e32 v22, v56
	v_mov_b32_e32 v23, v56
	v_mov_b32_e32 v8, v56
	v_mov_b32_e32 v9, v56
	v_mov_b32_e32 v10, v56
	v_mov_b32_e32 v11, v56
	v_mov_b32_e32 v0, v56
	v_mov_b32_e32 v1, v56
	v_mov_b32_e32 v2, v56
	v_mov_b32_e32 v3, v56
	v_mov_b32_e32 v12, v56
	v_mov_b32_e32 v13, v56
	v_mov_b32_e32 v14, v56
	v_mov_b32_e32 v15, v56
	v_mov_b32_e32 v4, v56
	v_mov_b32_e32 v5, v56
	v_mov_b32_e32 v6, v56
	v_mov_b32_e32 v7, v56
	v_mov_b32_e32 v116, v56
	v_mov_b32_e32 v117, v56
	v_mov_b32_e32 v118, v56
	v_mov_b32_e32 v119, v56
	v_mov_b32_e32 v120, v56
	v_mov_b32_e32 v121, v56
	v_mov_b32_e32 v122, v56
	v_mov_b32_e32 v123, v56
	v_mov_b32_e32 v124, v56
	v_mov_b32_e32 v125, v56
	v_mov_b32_e32 v126, v56
	v_mov_b32_e32 v127, v56
	v_mov_b32_e32 v128, v56
	v_mov_b32_e32 v129, v56
	v_mov_b32_e32 v130, v56
	v_mov_b32_e32 v131, v56
	v_mov_b32_e32 v132, v56
	v_mov_b32_e32 v133, v56
	v_mov_b32_e32 v134, v56
	v_mov_b32_e32 v135, v56
	v_mov_b32_e32 v136, v56
	v_mov_b32_e32 v137, v56
	v_mov_b32_e32 v138, v56
	v_mov_b32_e32 v139, v56
	v_mov_b32_e32 v140, v56
	v_mov_b32_e32 v141, v56
	v_mov_b32_e32 v142, v56
	v_mov_b32_e32 v143, v56
	v_mov_b32_e32 v144, v56
	v_mov_b32_e32 v145, v56
	v_mov_b32_e32 v146, v56
	v_mov_b32_e32 v147, v56
	v_mov_b32_e32 v148, v56
	v_mov_b32_e32 v149, v56
	v_mov_b32_e32 v150, v56
	v_mov_b32_e32 v151, v56
	v_mov_b32_e32 v152, v56
	v_mov_b32_e32 v153, v56
	v_mov_b32_e32 v154, v56
	v_mov_b32_e32 v155, v56
	v_mov_b32_e32 v156, v56
	v_mov_b32_e32 v157, v56
	v_mov_b32_e32 v158, v56
	v_mov_b32_e32 v159, v56
	v_mov_b32_e32 v160, v56
	v_mov_b32_e32 v161, v56
	v_mov_b32_e32 v162, v56
	v_mov_b32_e32 v163, v56
	v_mov_b32_e32 v164, v56
	v_mov_b32_e32 v165, v56
	v_mov_b32_e32 v166, v56
	v_mov_b32_e32 v167, v56
	v_mov_b32_e32 v172, v56
	v_mov_b32_e32 v173, v56
	v_mov_b32_e32 v174, v56
	v_mov_b32_e32 v175, v56
	v_mov_b32_e32 v176, v56
	v_mov_b32_e32 v177, v56
	v_mov_b32_e32 v178, v56
	v_mov_b32_e32 v179, v56
	v_mov_b32_e32 v180, v56
	v_mov_b32_e32 v181, v56
	v_mov_b32_e32 v182, v56
	v_mov_b32_e32 v183, v56
	s_mov_b32 s94, 0

.LBB0_538:
	v_and_b32_e32 v236, 15, v168
	v_lshrrev_b32_e32 v237, 1, v236
	v_bfe_u32 v238, v168, 4, 2
	v_xor_b32_e32 v237, v237, v238
	v_lshlrev_b32_e32 v237, 4, v237
	v_lshl_or_b32 v236, v236, 7, v237
	v_xor_b32_e32 v237, 64, v236
	v_add_u32_e32 v236, 16, v236
	v_add_u32_e32 v237, 16, v237
	v_bfe_u32 v238, v168, 7, 1
	v_lshl_add_u32 v240, v238, 13, v237
	v_lshl_add_u32 v238, v238, 13, v236
	v_bfe_u32 v239, v168, 6, 1
	v_lshl_add_u32 v241, v239, 13, v237
	v_lshl_add_u32 v239, v239, 13, v236
	v_lshrrev_b32_e32 v236, 3, v168
	v_lshrrev_b32_e32 v237, 4, v168
	v_xor_b32_e32 v237, v237, v168
	v_and_b32_e32 v237, 7, v237
	v_lshlrev_b32_e32 v237, 4, v237
	v_lshl_or_b32 v232, v236, 11, v237
	v_add_u32_e32 v233, 0x10000, v232
	v_add_u32_e32 v234, 0x20000, v232
	v_add_u32_e32 v235, 0x30000, v232
	s_load_dwordx2 s[90:91], s[0:1], 0xd8
	s_load_dwordx2 s[92:93], s[0:1], 0xc0
	v_lshrrev_b32_e32 v237, 6, v168
	s_nop 1
	v_readfirstlane_b32 s97, v237
	s_nop 3
	s_lshl_b32 s96, s97, 10
	s_add_u32 s96, s96, 16
	s_add_u32 s94, s61, s60
	s_cmp_lt_i32 s94, s62
	s_cselect_b32 s95, 1, 0
	s_cmp_lg_u64 s[12:13], 0
	s_cselect_b32 s95, 0, s95
	s_cmp_ge_u32 s94, 0x40
	s_cselect_b32 s97, 1, 0
	s_mul_i32 s100, s97, 0x40
	s_sub_u32 s100, s94, s100
	s_lshr_b32 s101, s100, 3
	s_and_b32 s100, s100, 7
	s_lshl_b32 s97, s97, 3
	s_add_u32 s100, s100, s97
	s_add_u32 s100, s100, s3
	s_cmp_lg_u32 s101, s48
	s_cselect_b32 s95, 0, s95
	s_cmp_eq_u32 s95, 1
	s_cselect_b32 s101, s100, s50
	s_mov_b32 s97, s101
	s_waitcnt lgkmcnt(0)
	s_lshl_b32 s94, s48, 18
	s_add_u32 s98, s92, s94
	s_addc_u32 s99, s93, 0
	s_lshl_b32 s101, s101, 18
	s_add_u32 s92, s90, s101
	s_addc_u32 s93, s91, 0
	s_lshl_b32 s94, s50, 18
	s_add_u32 s90, s90, s94
	s_addc_u32 s91, s91, 0
	s_mov_b64 s[100:101], s[90:91]
	s_mov_b64 s[90:91], s[98:99]
	s_mov_b64 s[98:99], s[92:93]
	s_mov_b64 s[92:93], s[100:101]
	s_waitcnt vmcnt(0)
	s_barrier
	s_add_u32 m0, s96, 0x0
	s_nop 0
	global_load_lds_dwordx4 v232, s[90:91]
	s_add_u32 m0, s96, 0x1000
	s_nop 0
	global_load_lds_dwordx4 v233, s[90:91]
	s_add_u32 m0, s96, 0x2000
	s_nop 0
	global_load_lds_dwordx4 v234, s[90:91]
	s_add_u32 m0, s96, 0x3000
	s_nop 0
	global_load_lds_dwordx4 v235, s[90:91]
	s_add_u32 m0, s96, 0x8000
	s_nop 0
	global_load_lds_dwordx4 v232, s[92:93]
	s_add_u32 m0, s96, 0x9000
	s_nop 0
	global_load_lds_dwordx4 v233, s[92:93]
	s_add_u32 m0, s96, 0xa000
	s_nop 0
	global_load_lds_dwordx4 v234, s[92:93]
	s_add_u32 m0, s96, 0xb000
	s_nop 0
	global_load_lds_dwordx4 v235, s[92:93]
	s_add_u32 m0, s96, 0xc000
	s_nop 0
	global_load_lds_dwordx4 v232, s[98:99]
	s_add_u32 m0, s96, 0xd000
	s_nop 0
	global_load_lds_dwordx4 v233, s[98:99]
	s_add_u32 m0, s96, 0xe000
	s_nop 0
	global_load_lds_dwordx4 v234, s[98:99]
	s_add_u32 m0, s96, 0xf000
	s_nop 0
	global_load_lds_dwordx4 v235, s[98:99]
	s_add_u32 s90, s90, 0x80
	s_addc_u32 s91, s91, 0
	s_add_u32 s92, s92, 0x80
	s_addc_u32 s93, s93, 0
	s_add_u32 s98, s98, 0x80
	s_addc_u32 s99, s99, 0
	v_mov_b32_e32 v0, 0
	v_mov_b32_e32 v1, v0
	v_mov_b32_e32 v2, v0
	v_mov_b32_e32 v3, v0
	v_mov_b32_e32 v4, v0
	v_mov_b32_e32 v5, v0
	v_mov_b32_e32 v6, v0
	v_mov_b32_e32 v7, v0
	v_mov_b32_e32 v8, v0
	v_mov_b32_e32 v9, v0
	v_mov_b32_e32 v10, v0
	v_mov_b32_e32 v11, v0
	v_mov_b32_e32 v12, v0
	v_mov_b32_e32 v13, v0
	v_mov_b32_e32 v14, v0
	v_mov_b32_e32 v15, v0
	v_mov_b32_e32 v16, v0
	v_mov_b32_e32 v17, v0
	v_mov_b32_e32 v18, v0
	v_mov_b32_e32 v19, v0
	v_mov_b32_e32 v20, v0
	v_mov_b32_e32 v21, v0
	v_mov_b32_e32 v22, v0
	v_mov_b32_e32 v23, v0
	v_mov_b32_e32 v24, v0
	v_mov_b32_e32 v25, v0
	v_mov_b32_e32 v26, v0
	v_mov_b32_e32 v27, v0
	v_mov_b32_e32 v28, v0
	v_mov_b32_e32 v29, v0
	v_mov_b32_e32 v30, v0
	v_mov_b32_e32 v31, v0
	v_mov_b32_e32 v32, v0
	v_mov_b32_e32 v33, v0
	v_mov_b32_e32 v34, v0
	v_mov_b32_e32 v35, v0
	v_mov_b32_e32 v36, v0
	v_mov_b32_e32 v37, v0
	v_mov_b32_e32 v38, v0
	v_mov_b32_e32 v39, v0
	v_mov_b32_e32 v40, v0
	v_mov_b32_e32 v41, v0
	v_mov_b32_e32 v42, v0
	v_mov_b32_e32 v43, v0
	v_mov_b32_e32 v44, v0
	v_mov_b32_e32 v45, v0
	v_mov_b32_e32 v46, v0
	v_mov_b32_e32 v47, v0
	v_mov_b32_e32 v48, v0
	v_mov_b32_e32 v49, v0
	v_mov_b32_e32 v50, v0
	v_mov_b32_e32 v51, v0
	v_mov_b32_e32 v52, v0
	v_mov_b32_e32 v53, v0
	v_mov_b32_e32 v54, v0
	v_mov_b32_e32 v55, v0
	v_mov_b32_e32 v56, v0
	v_mov_b32_e32 v57, v0
	v_mov_b32_e32 v58, v0
	v_mov_b32_e32 v59, v0
	v_mov_b32_e32 v60, v0
	v_mov_b32_e32 v61, v0
	v_mov_b32_e32 v62, v0
	v_mov_b32_e32 v63, v0
	v_mov_b32_e32 v64, v0
	v_mov_b32_e32 v65, v0
	v_mov_b32_e32 v66, v0
	v_mov_b32_e32 v67, v0
	v_mov_b32_e32 v68, v0
	v_mov_b32_e32 v69, v0
	v_mov_b32_e32 v70, v0
	v_mov_b32_e32 v71, v0
	v_mov_b32_e32 v72, v0
	v_mov_b32_e32 v73, v0
	v_mov_b32_e32 v74, v0
	v_mov_b32_e32 v75, v0
	v_mov_b32_e32 v76, v0
	v_mov_b32_e32 v77, v0
	v_mov_b32_e32 v78, v0
	v_mov_b32_e32 v79, v0
	v_mov_b32_e32 v80, v0
	v_mov_b32_e32 v81, v0
	v_mov_b32_e32 v82, v0
	v_mov_b32_e32 v83, v0
	v_mov_b32_e32 v84, v0
	v_mov_b32_e32 v85, v0
	v_mov_b32_e32 v86, v0
	v_mov_b32_e32 v87, v0
	v_mov_b32_e32 v88, v0
	v_mov_b32_e32 v89, v0
	v_mov_b32_e32 v90, v0
	v_mov_b32_e32 v91, v0
	v_mov_b32_e32 v92, v0
	v_mov_b32_e32 v93, v0
	v_mov_b32_e32 v94, v0
	v_mov_b32_e32 v95, v0
	v_mov_b32_e32 v96, v0
	v_mov_b32_e32 v97, v0
	v_mov_b32_e32 v98, v0
	v_mov_b32_e32 v99, v0
	v_mov_b32_e32 v100, v0
	v_mov_b32_e32 v101, v0
	v_mov_b32_e32 v102, v0
	v_mov_b32_e32 v103, v0
	v_mov_b32_e32 v104, v0
	v_mov_b32_e32 v105, v0
	v_mov_b32_e32 v106, v0
	v_mov_b32_e32 v107, v0
	v_mov_b32_e32 v108, v0
	v_mov_b32_e32 v109, v0
	v_mov_b32_e32 v110, v0
	v_mov_b32_e32 v111, v0
	v_mov_b32_e32 v112, v0
	v_mov_b32_e32 v113, v0
	v_mov_b32_e32 v114, v0
	v_mov_b32_e32 v115, v0
	v_mov_b32_e32 v116, v0
	v_mov_b32_e32 v117, v0
	v_mov_b32_e32 v118, v0
	v_mov_b32_e32 v119, v0
	v_mov_b32_e32 v120, v0
	v_mov_b32_e32 v121, v0
	v_mov_b32_e32 v122, v0
	v_mov_b32_e32 v123, v0
	v_mov_b32_e32 v124, v0
	v_mov_b32_e32 v125, v0
	v_mov_b32_e32 v126, v0
	v_mov_b32_e32 v127, v0
	s_mov_b32 s94, 0

.LBB0_664:
	v_lshrrev_b32_e32 v84, 3, v168
	v_lshrrev_b32_e32 v85, 4, v168
	v_xor_b32_e32 v85, v85, v168
	v_and_b32_e32 v85, 7, v85
	v_lshlrev_b32_e32 v85, 4, v85
	v_lshl_or_b32 v72, v84, 11, v85
	v_add_u32_e32 v73, 0x10000, v72
	v_add_u32_e32 v66, 0x20000, v72
	v_add_u32_e32 v67, 0x30000, v72
	s_load_dwordx2 s[90:91], s[0:1], 0xf0
	s_load_dwordx2 s[92:93], s[0:1], 0xc8
	v_lshrrev_b32_e32 v85, 6, v168
	s_nop 1
	v_readfirstlane_b32 s97, v85
	s_nop 3
	s_lshl_b32 s96, s97, 10
	s_add_u32 s96, s96, 16
	s_add_u32 s94, s61, s60
	s_cmp_lt_i32 s94, s62
	s_cselect_b32 s95, 1, 0
	s_cmp_lg_u64 s[12:13], 0
	s_cselect_b32 s95, 0, s95
	s_cmp_ge_u32 s94, 0x80
	s_cselect_b32 s97, 1, 0
	s_mul_i32 s100, s97, 0x80
	s_sub_u32 s100, s94, s100
	s_lshr_b32 s101, s100, 3
	s_and_b32 s100, s100, 7
	s_lshl_b32 s97, s97, 3
	s_add_u32 s100, s100, s97
	s_add_u32 s100, s100, s3
	s_cmp_lg_u32 s100, s50
	s_cselect_b32 s95, 0, s95
	s_cmp_eq_u32 s95, 1
	s_cselect_b32 s101, s101, s48
	s_mov_b32 s83, s101
	s_waitcnt lgkmcnt(0)
	s_lshl_b32 s101, s101, 18
	s_add_u32 s98, s92, s101
	s_addc_u32 s99, s93, 0
	s_lshl_b32 s94, s48, 18
	s_add_u32 s92, s92, s94
	s_addc_u32 s93, s93, 0
	s_lshl_b32 s94, s50, 18
	s_add_u32 s90, s90, s94
	s_addc_u32 s91, s91, 0
	s_waitcnt vmcnt(0)
	s_barrier
	s_add_u32 m0, s96, 0x0
	s_nop 0
	global_load_lds_dwordx4 v72, s[90:91]
	s_add_u32 m0, s96, 0x1000
	s_nop 0
	global_load_lds_dwordx4 v73, s[90:91]
	s_add_u32 m0, s96, 0x2000
	s_nop 0
	global_load_lds_dwordx4 v66, s[90:91]
	s_add_u32 m0, s96, 0x3000
	s_nop 0
	global_load_lds_dwordx4 v67, s[90:91]
	s_add_u32 m0, s96, 0x8000
	s_nop 0
	global_load_lds_dwordx4 v72, s[92:93]
	s_add_u32 m0, s96, 0x9000
	s_nop 0
	global_load_lds_dwordx4 v73, s[92:93]
	s_add_u32 m0, s96, 0xa000
	s_nop 0
	global_load_lds_dwordx4 v66, s[92:93]
	s_add_u32 m0, s96, 0xb000
	s_nop 0
	global_load_lds_dwordx4 v67, s[92:93]
	s_add_u32 m0, s96, 0xc000
	s_nop 0
	global_load_lds_dwordx4 v72, s[98:99]
	s_add_u32 m0, s96, 0xd000
	s_nop 0
	global_load_lds_dwordx4 v73, s[98:99]
	s_add_u32 m0, s96, 0xe000
	s_nop 0
	global_load_lds_dwordx4 v66, s[98:99]
	s_add_u32 m0, s96, 0xf000
	s_nop 0
	global_load_lds_dwordx4 v67, s[98:99]
	s_add_u32 s90, s90, 0x80
	s_addc_u32 s91, s91, 0
	s_add_u32 s92, s92, 0x80
	s_addc_u32 s93, s93, 0
	s_add_u32 s98, s98, 0x80
	s_addc_u32 s99, s99, 0
	v_mov_b32_e32 v0, 0
	v_mov_b32_e32 v1, v0
	v_mov_b32_e32 v2, v0
	v_mov_b32_e32 v3, v0
	v_mov_b32_e32 v4, v0
	v_mov_b32_e32 v5, v0
	v_mov_b32_e32 v6, v0
	v_mov_b32_e32 v7, v0
	v_mov_b32_e32 v8, v0
	v_mov_b32_e32 v9, v0
	v_mov_b32_e32 v10, v0
	v_mov_b32_e32 v11, v0
	v_mov_b32_e32 v12, v0
	v_mov_b32_e32 v13, v0
	v_mov_b32_e32 v14, v0
	v_mov_b32_e32 v15, v0
	v_mov_b32_e32 v16, v0
	v_mov_b32_e32 v17, v0
	v_mov_b32_e32 v18, v0
	v_mov_b32_e32 v19, v0
	v_mov_b32_e32 v20, v0
	v_mov_b32_e32 v21, v0
	v_mov_b32_e32 v22, v0
	v_mov_b32_e32 v23, v0
	v_mov_b32_e32 v24, v0
	v_mov_b32_e32 v25, v0
	v_mov_b32_e32 v26, v0
	v_mov_b32_e32 v27, v0
	v_mov_b32_e32 v28, v0
	v_mov_b32_e32 v29, v0
	v_mov_b32_e32 v30, v0
	v_mov_b32_e32 v31, v0
	v_mov_b32_e32 v32, v0
	v_mov_b32_e32 v33, v0
	v_mov_b32_e32 v34, v0
	v_mov_b32_e32 v35, v0
	v_mov_b32_e32 v36, v0
	v_mov_b32_e32 v37, v0
	v_mov_b32_e32 v38, v0
	v_mov_b32_e32 v39, v0
	v_mov_b32_e32 v40, v0
	v_mov_b32_e32 v41, v0
	v_mov_b32_e32 v42, v0
	v_mov_b32_e32 v43, v0
	v_mov_b32_e32 v44, v0
	v_mov_b32_e32 v45, v0
	v_mov_b32_e32 v46, v0
	v_mov_b32_e32 v47, v0
	v_mov_b32_e32 v48, v0
	v_mov_b32_e32 v49, v0
	v_mov_b32_e32 v50, v0
	v_mov_b32_e32 v51, v0
	v_mov_b32_e32 v52, v0
	v_mov_b32_e32 v53, v0
	v_mov_b32_e32 v54, v0
	v_mov_b32_e32 v55, v0
	v_mov_b32_e32 v56, v0
	v_mov_b32_e32 v57, v0
	v_mov_b32_e32 v58, v0
	v_mov_b32_e32 v59, v0
	v_mov_b32_e32 v60, v0
	v_mov_b32_e32 v61, v0
	v_mov_b32_e32 v62, v0
	v_mov_b32_e32 v63, v0
	v_mov_b32_e32 v116, v0
	v_mov_b32_e32 v117, v0
	v_mov_b32_e32 v118, v0
	v_mov_b32_e32 v119, v0
	v_mov_b32_e32 v120, v0
	v_mov_b32_e32 v121, v0
	v_mov_b32_e32 v122, v0
	v_mov_b32_e32 v123, v0
	v_mov_b32_e32 v124, v0
	v_mov_b32_e32 v125, v0
	v_mov_b32_e32 v126, v0
	v_mov_b32_e32 v127, v0
	v_mov_b32_e32 v128, v0
	v_mov_b32_e32 v129, v0
	v_mov_b32_e32 v130, v0
	v_mov_b32_e32 v131, v0
	v_mov_b32_e32 v132, v0
	v_mov_b32_e32 v133, v0
	v_mov_b32_e32 v134, v0
	v_mov_b32_e32 v135, v0
	v_mov_b32_e32 v136, v0
	v_mov_b32_e32 v137, v0
	v_mov_b32_e32 v138, v0
	v_mov_b32_e32 v139, v0
	v_mov_b32_e32 v140, v0
	v_mov_b32_e32 v141, v0
	v_mov_b32_e32 v142, v0
	v_mov_b32_e32 v143, v0
	v_mov_b32_e32 v148, v0
	v_mov_b32_e32 v149, v0
	v_mov_b32_e32 v150, v0
	v_mov_b32_e32 v151, v0
	v_mov_b32_e32 v152, v0
	v_mov_b32_e32 v153, v0
	v_mov_b32_e32 v154, v0
	v_mov_b32_e32 v155, v0
	v_mov_b32_e32 v156, v0
	v_mov_b32_e32 v157, v0
	v_mov_b32_e32 v158, v0
	v_mov_b32_e32 v159, v0
	v_mov_b32_e32 v160, v0
	v_mov_b32_e32 v161, v0
	v_mov_b32_e32 v162, v0
	v_mov_b32_e32 v163, v0
	v_mov_b32_e32 v172, v0
	v_mov_b32_e32 v173, v0
	v_mov_b32_e32 v174, v0
	v_mov_b32_e32 v175, v0
	v_mov_b32_e32 v176, v0
	v_mov_b32_e32 v177, v0
	v_mov_b32_e32 v178, v0
	v_mov_b32_e32 v179, v0
	v_mov_b32_e32 v180, v0
	v_mov_b32_e32 v181, v0
	v_mov_b32_e32 v182, v0
	v_mov_b32_e32 v183, v0
	v_mov_b32_e32 v184, v0
	v_mov_b32_e32 v185, v0
	v_mov_b32_e32 v186, v0
	v_mov_b32_e32 v187, v0
	v_mov_b32_e32 v188, v0
	v_mov_b32_e32 v189, v0
	v_mov_b32_e32 v190, v0
	v_mov_b32_e32 v191, v0
	s_mov_b32 s94, 0
